# v43 + one static s_setprio 1 for the younger wave half (waves 4-7) across the NSA attention phase, reset at its end
# baseline (speedup 1.0000x reference)
.LBB0_1045:
	s_cmpk_lt_u32 s85, 0x100
	s_cbranch_scc1 .Lnsa_prio_skip
	s_setprio 1

.LBB0_1337:
	s_setprio 0
	v_readlane_b32 s95, v251, 48
	v_readlane_b32 s97, v251, 49
